# PD fused epilogue: residual rows prefetched into L2 while the panel exchange is in flight
# baseline (speedup 1.0000x reference)
;     __device__ __forceinline__ void exchange(int e, float (&sv)[2][4], float (&rv)[2][4], const Unit& u, int wr, int wc, int fr, int fq, LAS unsigned char* lds, int wid, int lane) const {
;     ...
;         if (wid < 4 && lane == 0) __hip_atomic_fetch_add(cnt, 1u, __ATOMIC_RELAXED, __HIP_MEMORY_SCOPE_AGENT);
;         if (wid == 0) {
;             unsigned sp = 0;
;             while ((unsigned)__builtin_amdgcn_readfirstlane(__hip_atomic_load(cnt, __ATOMIC_RELAXED, __HIP_MEMORY_SCOPE_AGENT)) < 16u) { __builtin_amdgcn_s_sleep(2); if (++sp > (1u << 22)) break; }
;     __device__ __forceinline__ void fused(f32x4 (&acc)[2][2][4][2], const Unit& u, int wr, int wc, int fr, int fq, LAS unsigned char* lds, int wid, int lane) const {
;     ...
; #pragma unroll
;             for (int m = 0; m < 4; ++m) {
;                 const bf16_t* hrow = hb + (size_t)(row0 + ai * HALF + m * 16) * DM + col0;
;                 asm volatile("" : "+v"(hrow) : "v"(dep));
;                 const float r1 = rv[ai][m];
;                 float q = 0.f;
; #pragma unroll
;                 for (int bj = 0; bj < 2; ++bj) {
;                     const u32x4 hv = *(const u32x4*)(hrow + bj * HALF);
.LBB0_1422:
	s_or_b64 exec, exec, s[8:9]
	v_lshl_add_u32 v231, s28, 8, v1
	v_lshl_or_b32 v232, s26, 8, v208
	v_ashrrev_i32_e32 v233, 31, v232
	v_lshl_add_u64 v[232:233], v[232:233], 1, s[22:23]
	v_mov_b32_e32 v234, v231
	v_ashrrev_i32_e32 v235, 31, v231
	v_lshlrev_b64 v[234:235], 11, v[234:235]
	v_lshl_add_u64 v[232:233], v[232:233], 0, v[234:235]
	v_mov_b32_e32 v234, 0x8000
	v_mov_b32_e32 v235, 0
	global_load_dwordx4 v[248:251], v[232:233], off
	global_load_dwordx4 v[244:247], v[232:233], off offset:256
	v_lshl_add_u64 v[232:233], v[232:233], 0, v[234:235]
	global_load_dwordx4 v[248:251], v[232:233], off
	global_load_dwordx4 v[244:247], v[232:233], off offset:256
	v_lshl_add_u64 v[232:233], v[232:233], 0, v[234:235]
	global_load_dwordx4 v[248:251], v[232:233], off
	global_load_dwordx4 v[244:247], v[232:233], off offset:256
	v_lshl_add_u64 v[232:233], v[232:233], 0, v[234:235]
	global_load_dwordx4 v[248:251], v[232:233], off
	global_load_dwordx4 v[244:247], v[232:233], off offset:256
	v_mov_b32_e32 v234, 0x28000
	v_lshl_add_u64 v[232:233], v[232:233], 0, v[234:235]
	v_mov_b32_e32 v234, 0x8000
	global_load_dwordx4 v[248:251], v[232:233], off
	global_load_dwordx4 v[244:247], v[232:233], off offset:256
	v_lshl_add_u64 v[232:233], v[232:233], 0, v[234:235]
	global_load_dwordx4 v[248:251], v[232:233], off
	global_load_dwordx4 v[244:247], v[232:233], off offset:256
	v_lshl_add_u64 v[232:233], v[232:233], 0, v[234:235]
	global_load_dwordx4 v[248:251], v[232:233], off
	global_load_dwordx4 v[244:247], v[232:233], off offset:256
	v_lshl_add_u64 v[232:233], v[232:233], 0, v[234:235]
	global_load_dwordx4 v[248:251], v[232:233], off
	global_load_dwordx4 v[244:247], v[232:233], off offset:256
	v_cndmask_b32_e64 v146, 0, 1, s[20:21]
	v_cmp_ne_u32_e64 s[8:9], 1, v146
	s_andn2_b64 vcc, exec, s[20:21]
	s_cbranch_vccnz .LBB0_1432
	s_mov_b32 s27, 0x400001
	s_branch .LBB0_1425
